# local seams use a lightweight XCD-local barrier (plain flag stores + sc1 polling through the shared L2) instead of memory-side atomics
# speedup vs baseline: 1.0002x; 1.0002x over previous
_Z6mk_fwd4Args:
	s_mov_b32 s98, 0
	s_mov_b32 s99, 0
	s_load_dword s3, s[0:1], 0xa0
	s_load_dwordx8 s[88:95], s[0:1], 0x80
	v_and_b32_e32 v254, 0x3ff, v0
	s_add_u32 s6, s0, 0x98
	s_addc_u32 s7, s1, 0
	s_waitcnt lgkmcnt(0)
	v_writelane_b32 v255, s3, 0
	v_readfirstlane_b32 s3, v254
	v_cmp_gt_u32_e32 vcc, 2, v254
	s_nop 0
	v_writelane_b32 v255, s3, 1
	s_and_saveexec_b64 s[4:5], vcc
	v_lshl_add_u32 v1, v254, 2, 0
	v_add_u32_e32 v1, 0x23000, v1
	v_mov_b32_e32 v2, 0
	ds_write_b32 v1, v2
	s_or_b64 exec, exec, s[4:5]
	s_add_u32 s14, s90, 0x4000
	s_addc_u32 s15, s91, 0
	s_sub_i32 s3, s93, s92
	s_cmp_lt_i32 s3, 2
	s_mov_b32 s97, 0
	s_waitcnt lgkmcnt(0)
	s_barrier
	s_cbranch_scc1 .LBB0_7
	s_getreg_b32 s4, hwreg(HW_REG_XCC_ID, 0, 4)
	s_and_b32 s97, s4, 15
	v_cmp_eq_u32_e32 vcc, 0, v254
	s_and_saveexec_b64 s[4:5], vcc
	s_cbranch_execz .LBB0_6
	s_mov_b64 s[8:9], exec
	v_mbcnt_lo_u32_b32 v1, s8, 0
	v_mbcnt_hi_u32_b32 v1, s9, v1
	v_cmp_eq_u32_e32 vcc, 0, v1
	s_and_b64 s[10:11], exec, vcc
	s_mov_b64 exec, s[10:11]
	s_cbranch_execz .LBB0_6
	s_lshl_b32 s10, s97, 8
	s_bcnt1_i32_b64 s8, s[8:9]
	v_mov_b32_e32 v1, s10
	v_mov_b32_e32 v2, s8
	global_atomic_add v1, v2, s[14:15] offset:1024
	s_and_b32 s16, s2, 7
	s_lshl_b32 s16, s16, 3
	s_mov_b64 s[18:19], 1
	s_lshl_b64 s[18:19], s[18:19], s16
	s_lshl_b32 s16, s97, 3
	v_mov_b32_e32 v4, s18
	v_mov_b32_e32 v5, s19
	v_mov_b32_e32 v3, s16
	global_atomic_add_x2 v[6:7], v3, v[4:5], s[90:91] offset:256 sc0
	s_waitcnt vmcnt(0)

.LBB0_344:
	s_cmp_lt_i32 s92, 3
	s_cselect_b64 s[8:9], -1, 0
	s_cmp_gt_i32 s93, 2
	s_cselect_b64 s[0:1], -1, 0
	s_and_b64 s[0:1], s[8:9], s[0:1]
	s_andn2_b64 vcc, exec, s[0:1]
	s_cbranch_vccnz .LBB0_441
	s_andn2_b64 vcc, exec, s[10:11]
	s_cbranch_vccnz .LBB0_395
	s_waitcnt vmcnt(0)
	v_cmp_eq_u32_e32 vcc, 0, v254
	s_waitcnt vmcnt(0) lgkmcnt(0)
	s_barrier
	s_and_saveexec_b64 s[0:1], vcc
	s_cbranch_execz .LBB0_394
	s_cmp_eq_u32 s98, 1
	s_cbranch_scc0 .Lxfull_2
	s_add_i32 s99, s99, 1
	s_and_b32 s4, s2, 7
	s_lshl_b32 s4, s4, 8
	s_add_u32 s4, s90, s4
	s_addc_u32 s5, s91, 0
	s_lshr_b32 s3, s2, 3
	v_mov_b32_e32 v0, s99
	v_mov_b32_e32 v1, s3
	v_lshlrev_b32_e32 v1, 2, v1
	global_store_dword v1, v0, s[4:5] offset:512
	s_cmp_eq_u32 s3, 0
	s_cbranch_scc0 .Lxwait_2
	s_mov_b64 s[6:7], exec
	s_mov_b32 exec_lo, -1
	s_mov_b32 exec_hi, 0
	v_lshlrev_b32_e32 v2, 2, v251
	s_mov_b32 s3, 0
.Lxpoll_2:
	global_load_dword v3, v2, s[4:5] offset:512 sc1
	s_waitcnt vmcnt(0)
	v_cmp_le_u32_e32 vcc, s99, v3
	s_nop 3
	s_cmp_eq_u32 vcc_lo, -1
	s_cbranch_scc1 .Lxdone_2
	s_sleep 1
	s_add_i32 s3, s3, 1
	s_cmp_lt_u32 s3, 0x100000
	s_cbranch_scc1 .Lxpoll_2
.Lxdone_2:
	s_mov_b64 exec, s[6:7]
	v_mov_b32_e32 v1, 0
	global_store_dword v1, v0, s[4:5] offset:640
	s_branch .Lxfin_2
.Lxwait_2:
	v_mov_b32_e32 v1, 0
	s_mov_b32 s3, 0
.Lxpoll2_2:
	global_load_dword v3, v1, s[4:5] offset:640 sc1
	s_waitcnt vmcnt(0)
	v_cmp_le_u32_e32 vcc, s99, v3
	s_nop 3
	s_cmp_lg_u32 vcc_lo, 0
	s_cbranch_scc1 .Lxfin_2
	s_sleep 1
	s_add_i32 s3, s3, 1
	s_cmp_lt_u32 s3, 0x100000
	s_cbranch_scc1 .Lxpoll2_2
.Lxfin_2:
	s_waitcnt vmcnt(0)
	buffer_inv sc1
	s_waitcnt vmcnt(0)
	s_branch .LBB0_394
.Lxfull_2:
	s_add_i32 s3, 0, 0x23000
	v_mov_b32_e32 v0, s3
	s_waitcnt vmcnt(0) expcnt(0) lgkmcnt(0)
	ds_read_b32 v2, v0
	s_add_i32 s3, 0, 0x23004
	v_mov_b32_e32 v0, s3
	ds_read_b32 v0, v0
	s_waitcnt lgkmcnt(1)
	v_cmp_ne_u32_e32 vcc, 0, v2
	s_cbranch_vccnz .LBB0_362
	s_add_u32 s4, s90, 0x4200
	s_addc_u32 s5, s91, 0
	s_add_u32 s6, s90, 0x4400
	s_addc_u32 s7, s91, 0
	s_add_u32 s10, s90, 0x4500
	s_addc_u32 s11, s91, 0
	s_add_u32 s12, s90, 0x4600
	s_addc_u32 s13, s91, 0
	s_add_u32 s14, s90, 0x4700
	s_addc_u32 s15, s91, 0
	s_add_u32 s16, s90, 0x4800
	s_addc_u32 s17, s91, 0
	s_add_u32 s18, s90, 0x4900
	s_addc_u32 s19, s91, 0
	s_add_u32 s20, s90, 0x4a00
	s_addc_u32 s21, s91, 0
	s_add_u32 s22, s90, 0x4b00
	s_addc_u32 s23, s91, 0
	s_add_u32 s24, s90, 0x4c00
	s_addc_u32 s25, s91, 0
	s_add_u32 s26, s90, 0x4d00
	s_addc_u32 s27, s91, 0
	s_add_u32 s28, s90, 0x4e00
	s_addc_u32 s29, s91, 0
	s_add_u32 s30, s90, 0x4f00
	s_addc_u32 s31, s91, 0
	s_add_u32 s34, s90, 0x5000
	s_addc_u32 s35, s91, 0
	s_add_u32 s36, s90, 0x5100
	s_addc_u32 s37, s91, 0
	s_add_u32 s38, s90, 0x5200
	v_readlane_b32 s3, v255, 0
	s_addc_u32 s39, s91, 0
	s_mul_i32 s3, s95, s3
	s_add_u32 s40, s90, 0x5300
	s_mul_i32 s3, s3, s94
	s_addc_u32 s41, s91, 0
	s_mov_b32 s33, 1
	v_mov_b32_e32 v16, 0
	s_branch .LBB0_350

.LBB0_441:
	s_cmp_lt_i32 s92, 4
	s_cselect_b64 s[10:11], -1, 0
	s_cmp_gt_i32 s93, 3
	s_cselect_b64 s[0:1], -1, 0
	s_and_b64 s[0:1], s[10:11], s[0:1]
	s_andn2_b64 vcc, exec, s[0:1]
	s_cbranch_vccnz .LBB0_622
	s_andn2_b64 vcc, exec, s[8:9]
	s_cbranch_vccnz .LBB0_492
	s_waitcnt vmcnt(0)
	v_cmp_eq_u32_e32 vcc, 0, v254
	s_waitcnt vmcnt(0) lgkmcnt(0)
	s_barrier
	s_and_saveexec_b64 s[0:1], vcc
	s_cbranch_execz .LBB0_491
	s_cmp_eq_u32 s98, 1
	s_cbranch_scc0 .Lxfull_3
	s_add_i32 s99, s99, 1
	s_and_b32 s4, s2, 7
	s_lshl_b32 s4, s4, 8
	s_add_u32 s4, s90, s4
	s_addc_u32 s5, s91, 0
	s_lshr_b32 s3, s2, 3
	v_mov_b32_e32 v0, s99
	v_mov_b32_e32 v1, s3
	v_lshlrev_b32_e32 v1, 2, v1
	global_store_dword v1, v0, s[4:5] offset:512
	s_cmp_eq_u32 s3, 0
	s_cbranch_scc0 .Lxwait_3
	s_mov_b64 s[6:7], exec
	s_mov_b32 exec_lo, -1
	s_mov_b32 exec_hi, 0
	v_lshlrev_b32_e32 v2, 2, v251
	s_mov_b32 s3, 0

.Lxfull_3:
	s_add_i32 s3, 0, 0x23000
	v_mov_b32_e32 v0, s3
	s_waitcnt vmcnt(0) expcnt(0) lgkmcnt(0)
	ds_read_b32 v2, v0
	s_add_i32 s3, 0, 0x23004
	v_mov_b32_e32 v0, s3
	ds_read_b32 v0, v0
	s_waitcnt lgkmcnt(1)
	v_cmp_ne_u32_e32 vcc, 0, v2
	s_cbranch_vccnz .LBB0_459
	s_add_u32 s4, s90, 0x4200
	s_addc_u32 s5, s91, 0
	s_add_u32 s6, s90, 0x4400
	s_addc_u32 s7, s91, 0
	s_add_u32 s8, s90, 0x4500
	s_addc_u32 s9, s91, 0
	s_add_u32 s12, s90, 0x4600
	s_addc_u32 s13, s91, 0
	s_add_u32 s14, s90, 0x4700
	s_addc_u32 s15, s91, 0
	s_add_u32 s16, s90, 0x4800
	s_addc_u32 s17, s91, 0
	s_add_u32 s18, s90, 0x4900
	s_addc_u32 s19, s91, 0
	s_add_u32 s20, s90, 0x4a00
	s_addc_u32 s21, s91, 0
	s_add_u32 s22, s90, 0x4b00
	s_addc_u32 s23, s91, 0
	s_add_u32 s24, s90, 0x4c00
	s_addc_u32 s25, s91, 0
	s_add_u32 s26, s90, 0x4d00
	s_addc_u32 s27, s91, 0
	s_add_u32 s28, s90, 0x4e00
	s_addc_u32 s29, s91, 0
	s_add_u32 s30, s90, 0x4f00
	s_addc_u32 s31, s91, 0
	s_add_u32 s34, s90, 0x5000
	s_addc_u32 s35, s91, 0
	s_add_u32 s36, s90, 0x5100
	s_addc_u32 s37, s91, 0
	s_add_u32 s38, s90, 0x5200
	v_readlane_b32 s3, v255, 0
	s_addc_u32 s39, s91, 0
	s_mul_i32 s3, s95, s3
	s_add_u32 s40, s90, 0x5300
	s_mul_i32 s3, s3, s94
	s_addc_u32 s41, s91, 0
	s_mov_b32 s33, 1
	v_mov_b32_e32 v16, 0
	s_branch .LBB0_447

.LBB0_704:
	s_cmp_lt_i32 s92, 6
	s_cselect_b64 s[0:1], -1, 0
	s_cmp_gt_i32 s93, 5
	s_cselect_b64 s[4:5], -1, 0
	s_and_b64 s[4:5], s[0:1], s[4:5]
	v_readlane_b32 s64, v255, 4
	s_andn2_b64 vcc, exec, s[4:5]
	v_readlane_b32 s68, v255, 8
	v_readlane_b32 s69, v255, 9
	v_readlane_b32 s65, v255, 5
	v_readlane_b32 s66, v255, 6
	v_readlane_b32 s67, v255, 7
	v_readlane_b32 s70, v255, 10
	v_readlane_b32 s71, v255, 11
	v_readlane_b32 s72, v255, 12
	v_readlane_b32 s73, v255, 13
	v_readlane_b32 s74, v255, 14
	v_readlane_b32 s75, v255, 15
	v_readlane_b32 s76, v255, 16
	v_readlane_b32 s77, v255, 17
	v_readlane_b32 s78, v255, 18
	v_readlane_b32 s79, v255, 19
	s_cbranch_vccnz .LBB0_765
	s_andn2_b64 vcc, exec, s[80:81]
	s_cbranch_vccnz .LBB0_755
	s_waitcnt vmcnt(0)
	v_cmp_eq_u32_e32 vcc, 0, v254
	s_waitcnt vmcnt(0) lgkmcnt(0)
	s_barrier
	s_and_saveexec_b64 s[4:5], vcc
	s_cbranch_execz .LBB0_754
	s_cmp_eq_u32 s98, 1
	s_cbranch_scc0 .Lxfull_5
	s_add_i32 s99, s99, 1
	s_and_b32 s6, s2, 7
	s_lshl_b32 s6, s6, 8
	s_add_u32 s6, s90, s6
	s_addc_u32 s7, s91, 0
	s_lshr_b32 s3, s2, 3
	v_mov_b32_e32 v0, s99
	v_mov_b32_e32 v1, s3
	v_lshlrev_b32_e32 v1, 2, v1
	global_store_dword v1, v0, s[6:7] offset:512
	s_cmp_eq_u32 s3, 0
	s_cbranch_scc0 .Lxwait_5
	s_mov_b64 s[8:9], exec
	s_mov_b32 exec_lo, -1
	s_mov_b32 exec_hi, 0
	v_lshlrev_b32_e32 v2, 2, v251
	s_mov_b32 s3, 0
.Lxpoll_5:
	global_load_dword v3, v2, s[6:7] offset:512 sc1
	s_waitcnt vmcnt(0)
	v_cmp_le_u32_e32 vcc, s99, v3
	s_nop 3
	s_cmp_eq_u32 vcc_lo, -1
	s_cbranch_scc1 .Lxdone_5
	s_sleep 1
	s_add_i32 s3, s3, 1
	s_cmp_lt_u32 s3, 0x100000
	s_cbranch_scc1 .Lxpoll_5
.Lxdone_5:
	s_mov_b64 exec, s[8:9]
	v_mov_b32_e32 v1, 0
	global_store_dword v1, v0, s[6:7] offset:640
	s_branch .Lxfin_5

.Lxpoll2_5:
	global_load_dword v3, v1, s[6:7] offset:640 sc1
	s_waitcnt vmcnt(0)
	v_cmp_le_u32_e32 vcc, s99, v3
	s_nop 3
	s_cmp_lg_u32 vcc_lo, 0
	s_cbranch_scc1 .Lxfin_5
	s_sleep 1
	s_add_i32 s3, s3, 1
	s_cmp_lt_u32 s3, 0x100000
	s_cbranch_scc1 .Lxpoll2_5

.Lxfull_5:
	s_add_i32 s3, 0, 0x23000
	v_mov_b32_e32 v0, s3
	s_waitcnt vmcnt(0) expcnt(0) lgkmcnt(0)
	ds_read_b32 v2, v0
	s_add_i32 s3, 0, 0x23004
	v_mov_b32_e32 v0, s3
	ds_read_b32 v0, v0
	s_waitcnt lgkmcnt(1)
	v_cmp_ne_u32_e32 vcc, 0, v2
	s_cbranch_vccnz .LBB0_722
	s_add_u32 s6, s90, 0x4200
	s_addc_u32 s7, s91, 0
	s_add_u32 s8, s90, 0x4400
	s_addc_u32 s9, s91, 0
	s_add_u32 s10, s90, 0x4500
	s_addc_u32 s11, s91, 0
	s_add_u32 s12, s90, 0x4600
	s_addc_u32 s13, s91, 0
	s_add_u32 s14, s90, 0x4700
	s_addc_u32 s15, s91, 0
	s_add_u32 s16, s90, 0x4800
	s_addc_u32 s17, s91, 0
	s_add_u32 s18, s90, 0x4900
	s_addc_u32 s19, s91, 0
	s_add_u32 s20, s90, 0x4a00
	s_addc_u32 s21, s91, 0
	s_add_u32 s22, s90, 0x4b00
	s_addc_u32 s23, s91, 0
	s_add_u32 s24, s90, 0x4c00
	s_addc_u32 s25, s91, 0
	s_add_u32 s26, s90, 0x4d00
	s_addc_u32 s27, s91, 0
	s_add_u32 s28, s90, 0x4e00
	s_addc_u32 s29, s91, 0
	s_add_u32 s30, s90, 0x4f00
	s_addc_u32 s31, s91, 0
	s_add_u32 s34, s90, 0x5000
	s_addc_u32 s35, s91, 0
	s_add_u32 s36, s90, 0x5100
	s_addc_u32 s37, s91, 0
	s_add_u32 s38, s90, 0x5200
	v_readlane_b32 s3, v255, 0
	s_addc_u32 s39, s91, 0
	s_mul_i32 s3, s95, s3
	s_add_u32 s40, s90, 0x5300
	s_mul_i32 s3, s3, s94
	s_addc_u32 s41, s91, 0
	s_mov_b32 s33, 1
	v_mov_b32_e32 v16, 0
	s_branch .LBB0_710

.LBB0_765:
	s_cmp_lt_i32 s92, 7
	s_cselect_b64 s[40:41], -1, 0
	s_cmp_gt_i32 s93, 6
	s_cselect_b64 s[4:5], -1, 0
	s_and_b64 s[4:5], s[40:41], s[4:5]
	s_andn2_b64 vcc, exec, s[4:5]
	s_cbranch_vccnz .LBB0_890
	s_andn2_b64 vcc, exec, s[0:1]
	s_cbranch_vccnz .LBB0_816
	s_waitcnt vmcnt(0)
	v_cmp_eq_u32_e32 vcc, 0, v254
	s_waitcnt vmcnt(0) lgkmcnt(0)
	s_barrier
	s_and_saveexec_b64 s[0:1], vcc
	s_cbranch_execz .LBB0_815
	s_cmp_eq_u32 s98, 1
	s_cbranch_scc0 .Lxfull_6
	s_add_i32 s99, s99, 1
	s_and_b32 s4, s2, 7
	s_lshl_b32 s4, s4, 8
	s_add_u32 s4, s90, s4
	s_addc_u32 s5, s91, 0
	s_lshr_b32 s3, s2, 3
	v_mov_b32_e32 v0, s99
	v_mov_b32_e32 v1, s3
	v_lshlrev_b32_e32 v1, 2, v1
	global_store_dword v1, v0, s[4:5] offset:512
	s_cmp_eq_u32 s3, 0
	s_cbranch_scc0 .Lxwait_6
	s_mov_b64 s[6:7], exec
	s_mov_b32 exec_lo, -1
	s_mov_b32 exec_hi, 0
	v_lshlrev_b32_e32 v2, 2, v251
	s_mov_b32 s3, 0

.Lxfull_6:
	s_add_i32 s3, 0, 0x23000
	v_mov_b32_e32 v0, s3
	s_waitcnt vmcnt(0) expcnt(0) lgkmcnt(0)
	ds_read_b32 v2, v0
	s_add_i32 s3, 0, 0x23004
	v_mov_b32_e32 v0, s3
	ds_read_b32 v0, v0
	s_waitcnt lgkmcnt(1)
	v_cmp_ne_u32_e32 vcc, 0, v2
	s_cbranch_vccnz .LBB0_783
	s_add_u32 s4, s90, 0x4200
	s_addc_u32 s5, s91, 0
	s_add_u32 s6, s90, 0x4400
	s_addc_u32 s7, s91, 0
	s_add_u32 s8, s90, 0x4500
	s_addc_u32 s9, s91, 0
	s_add_u32 s10, s90, 0x4600
	s_addc_u32 s11, s91, 0
	s_add_u32 s12, s90, 0x4700
	s_addc_u32 s13, s91, 0
	s_add_u32 s14, s90, 0x4800
	s_addc_u32 s15, s91, 0
	s_add_u32 s16, s90, 0x4900
	s_addc_u32 s17, s91, 0
	s_add_u32 s18, s90, 0x4a00
	s_addc_u32 s19, s91, 0
	s_add_u32 s20, s90, 0x4b00
	s_addc_u32 s21, s91, 0
	s_add_u32 s22, s90, 0x4c00
	s_addc_u32 s23, s91, 0
	s_add_u32 s24, s90, 0x4d00
	s_addc_u32 s25, s91, 0
	s_add_u32 s26, s90, 0x4e00
	s_addc_u32 s27, s91, 0
	s_add_u32 s28, s90, 0x4f00
	s_addc_u32 s29, s91, 0
	s_add_u32 s30, s90, 0x5000
	s_addc_u32 s31, s91, 0
	s_add_u32 s34, s90, 0x5100
	s_addc_u32 s35, s91, 0
	s_add_u32 s36, s90, 0x5200
	v_readlane_b32 s3, v255, 0
	s_addc_u32 s37, s91, 0
	s_mul_i32 s3, s95, s3
	s_add_u32 s38, s90, 0x5300
	s_mul_i32 s3, s3, s94
	s_addc_u32 s39, s91, 0
	s_mov_b32 s33, 1
	v_mov_b32_e32 v16, 0
	s_branch .LBB0_771

.LBB0_983:
	s_cmp_lt_i32 s92, 9
	s_cselect_b64 s[10:11], -1, 0
	s_cmp_gt_i32 s93, 8
	s_cselect_b64 s[0:1], -1, 0
	s_and_b64 s[0:1], s[10:11], s[0:1]
	s_andn2_b64 vcc, exec, s[0:1]
	s_cbranch_vccnz .LBB0_1056
	s_andn2_b64 vcc, exec, s[6:7]
	s_cbranch_vccnz .LBB0_1034
	s_waitcnt vmcnt(0)
	v_cmp_eq_u32_e32 vcc, 0, v254
	s_waitcnt vmcnt(0) lgkmcnt(0)
	s_barrier
	s_and_saveexec_b64 s[0:1], vcc
	s_cbranch_execz .LBB0_1033
	s_cmp_eq_u32 s98, 1
	s_cbranch_scc0 .Lxfull_8
	s_add_i32 s99, s99, 1
	s_and_b32 s4, s2, 7
	s_lshl_b32 s4, s4, 8
	s_add_u32 s4, s90, s4
	s_addc_u32 s5, s91, 0
	s_lshr_b32 s3, s2, 3
	v_mov_b32_e32 v0, s99
	v_mov_b32_e32 v1, s3
	v_lshlrev_b32_e32 v1, 2, v1
	global_store_dword v1, v0, s[4:5] offset:512
	s_cmp_eq_u32 s3, 0
	s_cbranch_scc0 .Lxwait_8
	s_mov_b64 s[6:7], exec
	s_mov_b32 exec_lo, -1
	s_mov_b32 exec_hi, 0
	v_lshlrev_b32_e32 v2, 2, v251
	s_mov_b32 s3, 0

.LBB0_1056:
	s_cmp_lt_i32 s92, 10
	s_cselect_b64 s[8:9], -1, 0
	s_cmp_gt_i32 s93, 9
	s_cselect_b64 s[0:1], -1, 0
	s_and_b64 s[0:1], s[8:9], s[0:1]
	s_andn2_b64 vcc, exec, s[0:1]
	s_cbranch_vccnz .LBB0_1153
	s_andn2_b64 vcc, exec, s[10:11]
	s_cbranch_vccnz .LBB0_1107
	s_waitcnt vmcnt(0)
	v_cmp_eq_u32_e32 vcc, 0, v254
	s_waitcnt vmcnt(0) lgkmcnt(0)
	s_barrier
	s_and_saveexec_b64 s[0:1], vcc
	s_cbranch_execz .LBB0_1106
	s_cmp_eq_u32 s98, 1
	s_cbranch_scc0 .Lxfull_9
	s_add_i32 s99, s99, 1
	s_and_b32 s4, s2, 7
	s_lshl_b32 s4, s4, 8
	s_add_u32 s4, s90, s4
	s_addc_u32 s5, s91, 0
	s_lshr_b32 s3, s2, 3
	v_mov_b32_e32 v0, s99
	v_mov_b32_e32 v1, s3
	v_lshlrev_b32_e32 v1, 2, v1
	global_store_dword v1, v0, s[4:5] offset:512
	s_cmp_eq_u32 s3, 0
	s_cbranch_scc0 .Lxwait_9
	s_mov_b64 s[6:7], exec
	s_mov_b32 exec_lo, -1
	s_mov_b32 exec_hi, 0
	v_lshlrev_b32_e32 v2, 2, v251
	s_mov_b32 s3, 0

.LBB0_1153:
	s_cmp_lt_i32 s92, 11
	s_cselect_b64 s[6:7], -1, 0
	s_cmp_gt_i32 s93, 10
	s_cselect_b64 s[0:1], -1, 0
	s_and_b64 s[0:1], s[6:7], s[0:1]
	s_andn2_b64 vcc, exec, s[0:1]
	s_cbranch_vccnz .LBB0_1226
	s_andn2_b64 vcc, exec, s[8:9]
	s_cbranch_vccnz .LBB0_1204
	s_waitcnt vmcnt(0)
	v_cmp_eq_u32_e32 vcc, 0, v254
	s_waitcnt vmcnt(0) lgkmcnt(0)
	s_barrier
	s_and_saveexec_b64 s[0:1], vcc
	s_cbranch_execz .LBB0_1203
	s_cmp_eq_u32 s98, 1
	s_cbranch_scc0 .Lxfull_10
	s_add_i32 s99, s99, 1
	s_and_b32 s4, s2, 7
	s_lshl_b32 s4, s4, 8
	s_add_u32 s4, s90, s4
	s_addc_u32 s5, s91, 0
	s_lshr_b32 s3, s2, 3
	v_mov_b32_e32 v0, s99
	v_mov_b32_e32 v1, s3
	v_lshlrev_b32_e32 v1, 2, v1
	global_store_dword v1, v0, s[4:5] offset:512
	s_cmp_eq_u32 s3, 0
	s_cbranch_scc0 .Lxwait_10
	s_mov_b64 s[8:9], exec
	s_mov_b32 exec_lo, -1
	s_mov_b32 exec_hi, 0
	v_lshlrev_b32_e32 v2, 2, v251
	s_mov_b32 s3, 0

.Lxdone_10:
	s_mov_b64 exec, s[8:9]
	v_mov_b32_e32 v1, 0
	global_store_dword v1, v0, s[4:5] offset:640
	s_branch .Lxfin_10

.Lxfull_10:
	s_add_i32 s3, 0, 0x23000
	v_mov_b32_e32 v0, s3
	s_waitcnt vmcnt(0) expcnt(0) lgkmcnt(0)
	ds_read_b32 v2, v0
	s_add_i32 s3, 0, 0x23004
	v_mov_b32_e32 v0, s3
	ds_read_b32 v0, v0
	s_waitcnt lgkmcnt(1)
	v_cmp_ne_u32_e32 vcc, 0, v2
	s_cbranch_vccnz .LBB0_1171
	s_add_u32 s4, s90, 0x4200
	s_addc_u32 s5, s91, 0
	s_add_u32 s8, s90, 0x4400
	s_addc_u32 s9, s91, 0
	s_add_u32 s10, s90, 0x4500
	s_addc_u32 s11, s91, 0
	s_add_u32 s12, s90, 0x4600
	s_addc_u32 s13, s91, 0
	s_add_u32 s14, s90, 0x4700
	s_addc_u32 s15, s91, 0
	s_add_u32 s16, s90, 0x4800
	s_addc_u32 s17, s91, 0
	s_add_u32 s18, s90, 0x4900
	s_addc_u32 s19, s91, 0
	s_add_u32 s20, s90, 0x4a00
	s_addc_u32 s21, s91, 0
	s_add_u32 s22, s90, 0x4b00
	s_addc_u32 s23, s91, 0
	s_add_u32 s24, s90, 0x4c00
	s_addc_u32 s25, s91, 0
	s_add_u32 s26, s90, 0x4d00
	s_addc_u32 s27, s91, 0
	s_add_u32 s28, s90, 0x4e00
	s_addc_u32 s29, s91, 0
	s_add_u32 s30, s90, 0x4f00
	s_addc_u32 s31, s91, 0
	s_add_u32 s34, s90, 0x5000
	s_addc_u32 s35, s91, 0
	s_add_u32 s36, s90, 0x5100
	s_addc_u32 s37, s91, 0
	s_add_u32 s38, s90, 0x5200
	v_readlane_b32 s3, v255, 0
	s_addc_u32 s39, s91, 0
	s_mul_i32 s3, s95, s3
	s_add_u32 s40, s90, 0x5300
	s_mul_i32 s3, s3, s94
	s_addc_u32 s41, s91, 0
	s_mov_b32 s33, 1
	v_mov_b32_e32 v16, 0
	s_branch .LBB0_1159

.LBB0_1226:
	s_cmp_lt_i32 s92, 12
	s_cselect_b64 s[8:9], -1, 0
	s_cmp_gt_i32 s93, 11
	s_cselect_b64 s[0:1], -1, 0
	s_and_b64 s[0:1], s[8:9], s[0:1]
	s_andn2_b64 vcc, exec, s[0:1]
	s_cbranch_vccnz .LBB0_1323
	s_andn2_b64 vcc, exec, s[6:7]
	s_cbranch_vccnz .LBB0_1277
	s_waitcnt vmcnt(0)
	v_cmp_eq_u32_e32 vcc, 0, v254
	s_waitcnt vmcnt(0) lgkmcnt(0)
	s_barrier
	s_and_saveexec_b64 s[0:1], vcc
	s_cbranch_execz .LBB0_1276
	s_cmp_eq_u32 s98, 1
	s_cbranch_scc0 .Lxfull_11
	s_add_i32 s99, s99, 1
	s_and_b32 s4, s2, 7
	s_lshl_b32 s4, s4, 8
	s_add_u32 s4, s90, s4
	s_addc_u32 s5, s91, 0
	s_lshr_b32 s3, s2, 3
	v_mov_b32_e32 v0, s99
	v_mov_b32_e32 v1, s3
	v_lshlrev_b32_e32 v1, 2, v1
	global_store_dword v1, v0, s[4:5] offset:512
	s_cmp_eq_u32 s3, 0
	s_cbranch_scc0 .Lxwait_11
	s_mov_b64 s[6:7], exec
	s_mov_b32 exec_lo, -1
	s_mov_b32 exec_hi, 0
	v_lshlrev_b32_e32 v2, 2, v251
	s_mov_b32 s3, 0

.LBB0_1323:
	s_cmp_lt_i32 s92, 13
	s_cselect_b64 s[10:11], -1, 0
	s_cmp_gt_i32 s93, 12
	s_cselect_b64 s[0:1], -1, 0
	s_and_b64 s[0:1], s[10:11], s[0:1]
	s_andn2_b64 vcc, exec, s[0:1]
	s_cbranch_vccnz .LBB0_1504
	s_andn2_b64 vcc, exec, s[8:9]
	s_cbranch_vccnz .LBB0_1374
	s_waitcnt vmcnt(0)
	v_cmp_eq_u32_e32 vcc, 0, v254
	s_waitcnt vmcnt(0) lgkmcnt(0)
	s_barrier
	s_and_saveexec_b64 s[0:1], vcc
	s_cbranch_execz .LBB0_1373
	s_cmp_eq_u32 s98, 1
	s_cbranch_scc0 .Lxfull_12
	s_add_i32 s99, s99, 1
	s_and_b32 s4, s2, 7
	s_lshl_b32 s4, s4, 8
	s_add_u32 s4, s90, s4
	s_addc_u32 s5, s91, 0
	s_lshr_b32 s3, s2, 3
	v_mov_b32_e32 v0, s99
	v_mov_b32_e32 v1, s3
	v_lshlrev_b32_e32 v1, 2, v1
	global_store_dword v1, v0, s[4:5] offset:512
	s_cmp_eq_u32 s3, 0
	s_cbranch_scc0 .Lxwait_12
	s_mov_b64 s[6:7], exec
	s_mov_b32 exec_lo, -1
	s_mov_b32 exec_hi, 0
	v_lshlrev_b32_e32 v2, 2, v251
	s_mov_b32 s3, 0

.LBB0_1587:
	s_cmp_lt_i32 s92, 15
	s_cselect_b64 s[0:1], -1, 0
	s_cmp_gt_i32 s93, 14
	s_cselect_b64 s[4:5], -1, 0
	s_and_b64 s[4:5], s[0:1], s[4:5]
	v_readlane_b32 s64, v255, 4
	s_andn2_b64 vcc, exec, s[4:5]
	v_readlane_b32 s68, v255, 8
	v_readlane_b32 s69, v255, 9
	v_readlane_b32 s78, v255, 18
	v_readlane_b32 s79, v255, 19
	v_readlane_b32 s65, v255, 5
	v_readlane_b32 s66, v255, 6
	v_readlane_b32 s67, v255, 7
	v_readlane_b32 s70, v255, 10
	v_readlane_b32 s71, v255, 11
	v_readlane_b32 s72, v255, 12
	v_readlane_b32 s73, v255, 13
	v_readlane_b32 s74, v255, 14
	v_readlane_b32 s75, v255, 15
	v_readlane_b32 s76, v255, 16
	v_readlane_b32 s77, v255, 17
	s_cbranch_vccnz .LBB0_1648
	s_andn2_b64 vcc, exec, s[46:47]
	s_cbranch_vccnz .LBB0_1638
	s_waitcnt vmcnt(0)
	v_cmp_eq_u32_e32 vcc, 0, v254
	s_waitcnt vmcnt(0) lgkmcnt(0)
	s_barrier
	s_and_saveexec_b64 s[4:5], vcc
	s_cbranch_execz .LBB0_1637
	s_cmp_eq_u32 s98, 1
	s_cbranch_scc0 .Lxfull_14
	s_add_i32 s99, s99, 1
	s_and_b32 s6, s2, 7
	s_lshl_b32 s6, s6, 8
	s_add_u32 s6, s90, s6
	s_addc_u32 s7, s91, 0
	s_lshr_b32 s3, s2, 3
	v_mov_b32_e32 v0, s99
	v_mov_b32_e32 v1, s3
	v_lshlrev_b32_e32 v1, 2, v1
	global_store_dword v1, v0, s[6:7] offset:512
	s_cmp_eq_u32 s3, 0
	s_cbranch_scc0 .Lxwait_14
	s_mov_b64 s[8:9], exec
	s_mov_b32 exec_lo, -1
	s_mov_b32 exec_hi, 0
	v_lshlrev_b32_e32 v2, 2, v251
	s_mov_b32 s3, 0

.LBB0_1648:
	s_cmp_lt_i32 s92, 16
	s_cselect_b64 s[40:41], -1, 0
	s_cmp_gt_i32 s93, 15
	s_cselect_b64 s[4:5], -1, 0
	s_and_b64 s[4:5], s[40:41], s[4:5]
	s_andn2_b64 vcc, exec, s[4:5]
	s_cbranch_vccnz .LBB0_1773
	s_andn2_b64 vcc, exec, s[0:1]
	s_cbranch_vccnz .LBB0_1699
	s_waitcnt vmcnt(0)
	v_cmp_eq_u32_e32 vcc, 0, v254
	s_waitcnt vmcnt(0) lgkmcnt(0)
	s_barrier
	s_and_saveexec_b64 s[0:1], vcc
	s_cbranch_execz .LBB0_1698
	s_cmp_eq_u32 s98, 1
	s_cbranch_scc0 .Lxfull_15
	s_add_i32 s99, s99, 1
	s_and_b32 s4, s2, 7
	s_lshl_b32 s4, s4, 8
	s_add_u32 s4, s90, s4
	s_addc_u32 s5, s91, 0
	s_lshr_b32 s3, s2, 3
	v_mov_b32_e32 v0, s99
	v_mov_b32_e32 v1, s3
	v_lshlrev_b32_e32 v1, 2, v1
	global_store_dword v1, v0, s[4:5] offset:512
	s_cmp_eq_u32 s3, 0
	s_cbranch_scc0 .Lxwait_15
	s_mov_b64 s[6:7], exec
	s_mov_b32 exec_lo, -1
	s_mov_b32 exec_hi, 0
	v_lshlrev_b32_e32 v2, 2, v251
	s_mov_b32 s3, 0

.LBB0_1866:
	s_cmp_lt_i32 s92, 18
	s_cselect_b64 s[10:11], -1, 0
	s_cmp_gt_i32 s93, 17
	s_cselect_b64 s[0:1], -1, 0
	s_and_b64 s[0:1], s[10:11], s[0:1]
	s_andn2_b64 vcc, exec, s[0:1]
	s_cbranch_vccnz .LBB0_1939
	s_andn2_b64 vcc, exec, s[6:7]
	s_cbranch_vccnz .LBB0_1917
	s_waitcnt vmcnt(0)
	v_cmp_eq_u32_e32 vcc, 0, v254
	s_waitcnt vmcnt(0) lgkmcnt(0)
	s_barrier
	s_and_saveexec_b64 s[0:1], vcc
	s_cbranch_execz .LBB0_1916
	s_cmp_eq_u32 s98, 1
	s_cbranch_scc0 .Lxfull_17
	s_add_i32 s99, s99, 1
	s_and_b32 s4, s2, 7
	s_lshl_b32 s4, s4, 8
	s_add_u32 s4, s90, s4
	s_addc_u32 s5, s91, 0
	s_lshr_b32 s3, s2, 3
	v_mov_b32_e32 v0, s99
	v_mov_b32_e32 v1, s3
	v_lshlrev_b32_e32 v1, 2, v1
	global_store_dword v1, v0, s[4:5] offset:512
	s_cmp_eq_u32 s3, 0
	s_cbranch_scc0 .Lxwait_17
	s_mov_b64 s[6:7], exec
	s_mov_b32 exec_lo, -1
	s_mov_b32 exec_hi, 0
	v_lshlrev_b32_e32 v2, 2, v251
	s_mov_b32 s3, 0

.LBB0_1939:
	s_cmp_lt_i32 s92, 19
	s_cselect_b64 s[8:9], -1, 0
	s_cmp_gt_i32 s93, 18
	s_cselect_b64 s[0:1], -1, 0
	s_and_b64 s[0:1], s[8:9], s[0:1]
	s_andn2_b64 vcc, exec, s[0:1]
	s_cbranch_vccnz .LBB0_2036
	s_andn2_b64 vcc, exec, s[10:11]
	s_cbranch_vccnz .LBB0_1990
	s_waitcnt vmcnt(0)
	v_cmp_eq_u32_e32 vcc, 0, v254
	s_waitcnt vmcnt(0) lgkmcnt(0)
	s_barrier
	s_and_saveexec_b64 s[0:1], vcc
	s_cbranch_execz .LBB0_1989
	s_cmp_eq_u32 s98, 1
	s_cbranch_scc0 .Lxfull_18
	s_add_i32 s99, s99, 1
	s_and_b32 s4, s2, 7
	s_lshl_b32 s4, s4, 8
	s_add_u32 s4, s90, s4
	s_addc_u32 s5, s91, 0
	s_lshr_b32 s3, s2, 3
	v_mov_b32_e32 v0, s99
	v_mov_b32_e32 v1, s3
	v_lshlrev_b32_e32 v1, 2, v1
	global_store_dword v1, v0, s[4:5] offset:512
	s_cmp_eq_u32 s3, 0
	s_cbranch_scc0 .Lxwait_18
	s_mov_b64 s[6:7], exec
	s_mov_b32 exec_lo, -1
	s_mov_b32 exec_hi, 0
	v_lshlrev_b32_e32 v2, 2, v251
	s_mov_b32 s3, 0

.LBB0_2036:
	s_cmp_lt_i32 s92, 20
	s_cselect_b64 s[0:1], -1, 0
	s_cmp_gt_i32 s93, 19
	s_cselect_b64 s[4:5], -1, 0
	s_and_b64 s[0:1], s[0:1], s[4:5]
	s_andn2_b64 vcc, exec, s[0:1]
	s_cbranch_vccnz .LBB0_2090
	s_andn2_b64 vcc, exec, s[8:9]
	s_cbranch_vccnz .LBB0_2087
	s_waitcnt vmcnt(0)
	v_cmp_eq_u32_e32 vcc, 0, v254
	s_waitcnt vmcnt(0) lgkmcnt(0)
	s_barrier
	s_and_saveexec_b64 s[0:1], vcc
	s_cbranch_execz .LBB0_2086
	s_cmp_eq_u32 s98, 1
	s_cbranch_scc0 .Lxfull_19
	s_add_i32 s99, s99, 1
	s_and_b32 s4, s2, 7
	s_lshl_b32 s4, s4, 8
	s_add_u32 s4, s90, s4
	s_addc_u32 s5, s91, 0
	s_lshr_b32 s3, s2, 3
	v_mov_b32_e32 v0, s99
	v_mov_b32_e32 v1, s3
	v_lshlrev_b32_e32 v1, 2, v1
	global_store_dword v1, v0, s[4:5] offset:512
	s_cmp_eq_u32 s3, 0
	s_cbranch_scc0 .Lxwait_19
	s_mov_b64 s[6:7], exec
	s_mov_b32 exec_lo, -1
	s_mov_b32 exec_hi, 0
	v_lshlrev_b32_e32 v2, 2, v251
	s_mov_b32 s3, 0
